# attention phase: one static s_setprio 1 for waves 4-7 (younger half) per unit, reset to 0 at the grid barrier; on top of v17
# baseline (speedup 1.0000x reference)
.LBB0_73:
	s_or_b64 exec, exec, s[4:5]
	s_ashr_i32 s3, s2, 31
	s_ashr_i32 s11, s46, 6
	s_cmp_ge_u32 s11, 4
	s_cbranch_scc0 .Lattn_noprio
	s_setprio 1
.Lattn_noprio:
	s_lshl_b64 s[4:5], s[2:3], 13
	s_ashr_i32 s6, s19, 31
	s_add_u32 s4, s4, s19
	s_addc_u32 s5, s5, s6
	s_lshl_b32 s21, s11, 5
	s_ashr_i32 s7, s21, 31
	s_add_u32 s6, s4, s21
	s_addc_u32 s7, s5, s7
	s_lshl_b32 s12, s12, 6
	s_ashr_i32 s13, s12, 31
	s_lshl_b64 s[4:5], s[2:3], 24
	s_add_u32 s14, s27, s4
	s_addc_u32 s15, s29, s5
	s_lshl_b64 s[2:3], s[6:7], 11
	s_add_u32 s2, s23, s2
	s_addc_u32 s3, s24, s3
	s_lshl_b64 s[12:13], s[12:13], 1
	s_add_u32 s6, s2, s12
	s_addc_u32 s7, s3, s13
	s_add_u32 s2, s14, s12
	s_addc_u32 s3, s15, s13
	s_add_u32 s14, s25, s4
	s_addc_u32 s15, s26, s5
	v_and_b32_e32 v193, 63, v68
	s_add_u32 s14, s14, s12
	s_addc_u32 s15, s15, s13
	v_lshlrev_b32_e32 v180, 11, v193
	v_mov_b32_e32 v181, v99
	v_lshl_add_u64 v[0:1], s[14:15], 0, v[180:181]
	s_lshl_b32 s14, s11, 3
	s_ashr_i32 s15, s14, 31
	s_lshl_b32 s16, s11, 4
	v_bfe_u32 v188, v68, 2, 4
	v_lshl_add_u64 v[64:65], s[14:15], 1, v[0:1]
	v_and_or_b32 v0, s16, 48, v188
	v_lshlrev_b32_e32 v98, 11, v0
	v_lshl_add_u64 v[0:1], s[2:3], 0, v[98:99]
	s_ashr_i32 s2, s46, 3
	s_and_b32 s16, s2, 0xffffffe0
	s_ashr_i32 s17, s16, 31
	s_lshl_b32 s18, s11, 10
	v_lshlrev_b32_e32 v2, 3, v68
	s_cmp_lg_u32 0, -1
	s_waitcnt lgkmcnt(0)
	v_and_b32_e32 v224, 24, v2
	s_cselect_b32 s2, 0, 0
	v_lshl_add_u64 v[0:1], s[16:17], 1, v[0:1]
	v_lshlrev_b32_e32 v98, 1, v224
	s_add_i32 s42, s18, s2
	s_mov_b32 s2, m0
	s_mov_b32 m0, s42
	s_nop 0
	global_load_lds_dwordx4 v[64:65], off
	s_mov_b32 m0, s2
	v_lshl_add_u64 v[66:67], v[0:1], 0, v[98:99]
	s_add_i32 s43, s42, 0x6000
	s_mov_b32 s2, m0
	s_mov_b32 m0, s43
	s_nop 0
	global_load_lds_dwordx4 v[66:67], off
	s_mov_b32 m0, s2
	s_mov_b64 s[2:3], 0x20000
	v_and_b32_e32 v197, 31, v68
	v_lshl_add_u64 v[0:1], v[64:65], 0, s[2:3]
	v_bfe_u32 v223, v68, 5, 1
	s_add_i32 s2, s42, 0x2000
	s_mov_b32 s3, m0
	s_mov_b32 m0, s2
	s_nop 0
	global_load_lds_dwordx4 v[0:1], off
	s_mov_b32 m0, s3
	v_lshlrev_b32_e32 v0, 11, v197
	v_lshl_or_b32 v98, v223, 4, v0
	v_lshl_add_u64 v[0:1], s[6:7], 0, v[98:99]
	flat_load_dwordx4 v[132:135], v[0:1]
	flat_load_dwordx4 v[124:127], v[0:1] offset:32
	flat_load_dwordx4 v[116:119], v[0:1] offset:64
	flat_load_dwordx4 v[108:111], v[0:1] offset:96
	s_add_i32 s2, s42, 0x4000
	v_lshl_add_u64 v[0:1], v[64:65], 0, s[68:69]
	s_mov_b32 s3, m0
	s_mov_b32 m0, s2
	s_nop 0
	global_load_lds_dwordx4 v[0:1], off
	s_mov_b32 m0, s3
	v_lshl_add_u32 v44, v197, 2, 0
	s_waitcnt vmcnt(8)
	s_and_saveexec_b64 s[96:97], s[56:57]
	s_cbranch_execz .Lab0
	v_lshl_add_u32 v0, v68, 4, 0
	v_add_u32_e32 v0, 0x14800, v0
	ds_write_b128 v0, v[238:241]

.LBB0_1163:
	s_setprio 0
	s_waitcnt vmcnt(0)
	s_waitcnt vmcnt(0) lgkmcnt(0)
	s_barrier
	s_and_saveexec_b64 s[0:1], s[2:3]
	s_cbranch_execnz .LBB0_1164
	s_getpc_b64 s[98:99]
